# v65 + attention QK blocks: dead accumulator zeroing (80 v_mov/unit) removed, the four K-fragment ds_read_b128 of each block issued together with counted lgkmcnt waits
# speedup vs baseline: 1.0032x; 1.0004x over previous
; #define LAS __attribute__((address_space(3)))
; #define MFMA32(a, b, c) __builtin_amdgcn_mfma_f32_32x32x16_bf16((a), (b), (c), 0, 0, 0)
; DEV void attn_compute(const AttnU& a, const bf16x8 (&qf)[4], int tq, bf16_t* OG, float* LSE, LAS unsigned char* lds, int tid) {
;     ...
;     for (int sb = 0; sb < 5; ++sb) {
;         const int sbk = wave + sb, mb = a.mu0 - 64 + 32 * sbk;
;         vb[sb] = (mb >= 0) && (mb < a.Mg);
;         f32x16 acc;
; #pragma unroll
;         for (int i = 0; i < 16; ++i) acc[i] = 0.f;
;         if (vb[sb]) {
;             const LAS unsigned char* kp = lds + AT_K_OFF + (32 * sbk + n) * AT_KP + 16 * hl;
; #pragma unroll
;             for (int ks = 0; ks < 4; ++ks) { const bf16x8 kf = *(const LAS bf16x8*)(kp + 32 * ks); acc = MFMA32(kf, qf[ks], acc); }
.LBB0_651:
	s_mul_hi_i32 s2, s10, 0x2aaaaaab
	s_lshr_b32 s3, s2, 31
	s_ashr_i32 s2, s2, 6
	s_add_i32 s28, s2, s3
	s_mul_i32 s2, s28, 0xfffffe80
	s_add_i32 s30, s10, s2
	s_ashr_i32 s41, s30, 7
	s_lshl_b32 s10, s41, 1
	s_lshr_b32 s2, 16, s10
	s_and_b32 s19, s30, 15
	s_add_i32 s2, s2, -1
	s_and_b32 s2, s2, s19
	s_lshl_b32 s44, s2, 8
	v_ashrrev_i32_e32 v78, 6, v146
	s_sub_i32 s42, s44, 64
	v_lshlrev_b32_e32 v21, 5, v78
	s_lshr_b32 s29, 0x1000, s10
	v_add_u32_e32 v0, s42, v21
	v_bfe_u32 v47, v146, 5, 1
	v_cmp_lt_i32_e32 vcc, -1, v0
	v_cmp_gt_i32_e64 s[36:37], s29, v0
	v_lshl_add_u32 v46, v47, 4, 0
	s_and_b64 s[2:3], vcc, s[36:37]
	s_and_saveexec_b64 s[6:7], s[2:3]
	s_cbranch_execz .LBB0_653
	v_or_b32_e32 v0, v21, v147
	v_mad_u64_u32 v[52:53], s[34:35], v0, s48, v[46:47]
	ds_read_b128 v[0:3], v52
	ds_read_b128 v[172:175], v52 offset:32
	ds_read_b128 v[176:179], v52 offset:64
	ds_read_b128 v[180:183], v52 offset:96
	s_waitcnt lgkmcnt(3)
	v_mfma_f32_32x32x16_bf16 v[0:15], v[0:3], v[66:69], 0
	s_waitcnt lgkmcnt(2)
	v_mfma_f32_32x32x16_bf16 v[0:15], v[172:175], v[62:65], v[0:15]
	s_waitcnt lgkmcnt(1)
	v_mfma_f32_32x32x16_bf16 v[0:15], v[176:179], v[58:61], v[0:15]
	s_waitcnt lgkmcnt(0)
	v_mfma_f32_32x32x16_bf16 v[0:15], v[180:183], v[54:57], v[0:15]

; #define LAS __attribute__((address_space(3)))
; #define MFMA32(a, b, c) __builtin_amdgcn_mfma_f32_32x32x16_bf16((a), (b), (c), 0, 0, 0)
; DEV void attn_compute(const AttnU& a, const bf16x8 (&qf)[4], int tq, bf16_t* OG, float* LSE, LAS unsigned char* lds, int tid) {
;     ...
;     for (int sb = 0; sb < 5; ++sb) {
;         const int sbk = wave + sb, mb = a.mu0 - 64 + 32 * sbk;
;         vb[sb] = (mb >= 0) && (mb < a.Mg);
;         f32x16 acc;
; #pragma unroll
;         for (int i = 0; i < 16; ++i) acc[i] = 0.f;
;         if (vb[sb]) {
;             const LAS unsigned char* kp = lds + AT_K_OFF + (32 * sbk + n) * AT_KP + 16 * hl;
; #pragma unroll
;             for (int ks = 0; ks < 4; ++ks) { const bf16x8 kf = *(const LAS bf16x8*)(kp + 32 * ks); acc = MFMA32(kf, qf[ks], acc); }
.LBB0_685:
	v_add_u32_e32 v149, 1, v78
	v_lshlrev_b32_e32 v83, 5, v149
	v_add_u32_e32 v0, s42, v83
	v_cmp_lt_i32_e32 vcc, -1, v0
	v_cmp_gt_i32_e64 s[36:37], s29, v0
	s_and_b64 s[6:7], vcc, s[36:37]
	s_and_saveexec_b64 s[30:31], s[6:7]
	s_cbranch_execz .LBB0_687
	v_or_b32_e32 v0, v83, v147
	v_mad_u64_u32 v[88:89], s[34:35], v0, s48, v[46:47]
	ds_read_b128 v[0:3], v88
	ds_read_b128 v[172:175], v88 offset:32
	ds_read_b128 v[176:179], v88 offset:64
	ds_read_b128 v[180:183], v88 offset:96
	s_waitcnt lgkmcnt(3)
	v_mfma_f32_32x32x16_bf16 v[0:15], v[0:3], v[66:69], 0
	s_waitcnt lgkmcnt(2)
	v_mfma_f32_32x32x16_bf16 v[0:15], v[172:175], v[62:65], v[0:15]
	s_waitcnt lgkmcnt(1)
	v_mfma_f32_32x32x16_bf16 v[0:15], v[176:179], v[58:61], v[0:15]
	s_waitcnt lgkmcnt(0)
	v_mfma_f32_32x32x16_bf16 v[0:15], v[180:183], v[54:57], v[0:15]

; #define LAS __attribute__((address_space(3)))
; #define MFMA32(a, b, c) __builtin_amdgcn_mfma_f32_32x32x16_bf16((a), (b), (c), 0, 0, 0)
; DEV void attn_compute(const AttnU& a, const bf16x8 (&qf)[4], int tq, bf16_t* OG, float* LSE, LAS unsigned char* lds, int tid) {
;     ...
;     for (int sb = 0; sb < 5; ++sb) {
;         const int sbk = wave + sb, mb = a.mu0 - 64 + 32 * sbk;
;         vb[sb] = (mb >= 0) && (mb < a.Mg);
;         f32x16 acc;
; #pragma unroll
;         for (int i = 0; i < 16; ++i) acc[i] = 0.f;
;         if (vb[sb]) {
;             const LAS unsigned char* kp = lds + AT_K_OFF + (32 * sbk + n) * AT_KP + 16 * hl;
; #pragma unroll
;             for (int ks = 0; ks < 4; ++ks) { const bf16x8 kf = *(const LAS bf16x8*)(kp + 32 * ks); acc = MFMA32(kf, qf[ks], acc); }
.LBB0_719:
	v_add_u32_e32 v150, 2, v78
	v_lshlrev_b32_e32 v99, 5, v150
	v_add_u32_e32 v0, s42, v99
	v_cmp_lt_i32_e32 vcc, -1, v0
	v_cmp_gt_i32_e64 s[36:37], s29, v0
	s_and_b64 s[30:31], vcc, s[36:37]
	s_and_saveexec_b64 s[34:35], s[30:31]
	s_cbranch_execz .LBB0_721
	v_or_b32_e32 v0, v99, v147
	v_mad_u64_u32 v[104:105], s[36:37], v0, s48, v[46:47]
	ds_read_b128 v[0:3], v104
	ds_read_b128 v[172:175], v104 offset:32
	ds_read_b128 v[176:179], v104 offset:64
	ds_read_b128 v[180:183], v104 offset:96
	s_waitcnt lgkmcnt(3)
	v_mfma_f32_32x32x16_bf16 v[0:15], v[0:3], v[66:69], 0
	s_waitcnt lgkmcnt(2)
	v_mfma_f32_32x32x16_bf16 v[0:15], v[172:175], v[62:65], v[0:15]
	s_waitcnt lgkmcnt(1)
	v_mfma_f32_32x32x16_bf16 v[0:15], v[176:179], v[58:61], v[0:15]
	s_waitcnt lgkmcnt(0)
	v_mfma_f32_32x32x16_bf16 v[0:15], v[180:183], v[54:57], v[0:15]

; #define LAS __attribute__((address_space(3)))
; #define MFMA32(a, b, c) __builtin_amdgcn_mfma_f32_32x32x16_bf16((a), (b), (c), 0, 0, 0)
; DEV void attn_compute(const AttnU& a, const bf16x8 (&qf)[4], int tq, bf16_t* OG, float* LSE, LAS unsigned char* lds, int tid) {
;     ...
;     for (int sb = 0; sb < 5; ++sb) {
;         const int sbk = wave + sb, mb = a.mu0 - 64 + 32 * sbk;
;         vb[sb] = (mb >= 0) && (mb < a.Mg);
;         f32x16 acc;
; #pragma unroll
;         for (int i = 0; i < 16; ++i) acc[i] = 0.f;
;         if (vb[sb]) {
;             const LAS unsigned char* kp = lds + AT_K_OFF + (32 * sbk + n) * AT_KP + 16 * hl;
; #pragma unroll
;             for (int ks = 0; ks < 4; ++ks) { const bf16x8 kf = *(const LAS bf16x8*)(kp + 32 * ks); acc = MFMA32(kf, qf[ks], acc); }
.LBB0_753:
	v_add_u32_e32 v151, 3, v78
	v_lshlrev_b32_e32 v152, 5, v151
	v_add_u32_e32 v0, s42, v152
	v_cmp_lt_i32_e32 vcc, -1, v0
	v_cmp_gt_i32_e64 s[36:37], s29, v0
	s_and_b64 s[34:35], vcc, s[36:37]
	s_and_saveexec_b64 s[36:37], s[34:35]
	s_cbranch_execz .LBB0_755
	v_or_b32_e32 v0, v152, v147
	v_mad_u64_u32 v[162:163], s[46:47], v0, s48, v[46:47]
	ds_read_b128 v[0:3], v162
	ds_read_b128 v[172:175], v162 offset:32
	ds_read_b128 v[176:179], v162 offset:64
	ds_read_b128 v[180:183], v162 offset:96
	s_waitcnt lgkmcnt(3)
	v_mfma_f32_32x32x16_bf16 v[0:15], v[0:3], v[66:69], 0
	s_waitcnt lgkmcnt(2)
	v_mfma_f32_32x32x16_bf16 v[0:15], v[172:175], v[62:65], v[0:15]
	s_waitcnt lgkmcnt(1)
	v_mfma_f32_32x32x16_bf16 v[0:15], v[176:179], v[58:61], v[0:15]
	s_waitcnt lgkmcnt(0)
	v_mfma_f32_32x32x16_bf16 v[0:15], v[180:183], v[54:57], v[0:15]

; #define LAS __attribute__((address_space(3)))
; #define MFMA32(a, b, c) __builtin_amdgcn_mfma_f32_32x32x16_bf16((a), (b), (c), 0, 0, 0)
; DEV void attn_compute(const AttnU& a, const bf16x8 (&qf)[4], int tq, bf16_t* OG, float* LSE, LAS unsigned char* lds, int tid) {
;     ...
;     for (int sb = 0; sb < 5; ++sb) {
;         const int sbk = wave + sb, mb = a.mu0 - 64 + 32 * sbk;
;         vb[sb] = (mb >= 0) && (mb < a.Mg);
;         f32x16 acc;
; #pragma unroll
;         for (int i = 0; i < 16; ++i) acc[i] = 0.f;
;         if (vb[sb]) {
;             const LAS unsigned char* kp = lds + AT_K_OFF + (32 * sbk + n) * AT_KP + 16 * hl;
; #pragma unroll
;             for (int ks = 0; ks < 4; ++ks) { const bf16x8 kf = *(const LAS bf16x8*)(kp + 32 * ks); acc = MFMA32(kf, qf[ks], acc); }
.LBB0_787:
	v_add_u32_e32 v152, 4, v78
	v_lshlrev_b32_e32 v78, 5, v152
	v_add_u32_e32 v0, s42, v78
	v_cmp_lt_i32_e32 vcc, -1, v0
	v_cmp_gt_i32_e64 s[36:37], s29, v0
	s_and_b64 s[36:37], vcc, s[36:37]
	s_and_saveexec_b64 s[42:43], s[36:37]
	s_cbranch_execz .LBB0_789
	v_or_b32_e32 v0, v78, v147
	v_mad_u64_u32 v[168:169], s[46:47], v0, s48, v[46:47]
	ds_read_b128 v[0:3], v168
	ds_read_b128 v[172:175], v168 offset:32
	ds_read_b128 v[176:179], v168 offset:64
	ds_read_b128 v[180:183], v168 offset:96
	s_waitcnt lgkmcnt(3)
	v_mfma_f32_32x32x16_bf16 v[0:15], v[0:3], v[66:69], 0
	s_waitcnt lgkmcnt(2)
	v_mfma_f32_32x32x16_bf16 v[0:15], v[172:175], v[62:65], v[0:15]
	s_waitcnt lgkmcnt(1)
	v_mfma_f32_32x32x16_bf16 v[0:15], v[176:179], v[58:61], v[0:15]
	s_waitcnt lgkmcnt(0)
	v_mfma_f32_32x32x16_bf16 v[0:15], v[180:183], v[54:57], v[0:15]
